# stick-breaking loop: next K/V tile prefetched into spare VGPRs after the LDS writes; plus earlier attention copy/VALU trims
# baseline (speedup 1.0000x reference)
; #define LAS __attribute__((address_space(3)))
; DI void sb_unit(const Params& P, LAS char* lds, int b, int hd, int qb, int wave, int lane) {
;     ...
;     const bf16_t* Kg = hb + (size_t)b * SEQ * NIN + C_SBK + 64 * hd; const bf16_t* Vg = hb + (size_t)b * SEQ * NIN + C_SBV + 64 * hd;
;     LAS char* Kl = lds + wave * 9216; LAS char* Vl = Kl + 4608;
;     f32x16 o[2]; zero_o(o);
;     float carry = 0.f;
;     ...
;         const int kbase = 32 * st;
;         u32x4 kr[4], vr[4];
; #pragma unroll
;         for (int jj = 0; jj < 4; ++jj) { const int ch = lane + 64 * jj, key = ch >> 3, cc = ch & 7;
;             kr[jj] = *(const u32x4*)(Kg + (size_t)(kbase + key) * NIN + 8 * cc); vr[jj] = *(const u32x4*)(Vg + (size_t)(kbase + key) * NIN + 8 * cc); }
;         asm volatile("" ::: "memory");
; #pragma unroll
;         for (int jj = 0; jj < 4; ++jj) { const int ch = lane + 64 * jj, key = ch >> 3, cc = ch & 7;
;             *(LAS u32x4*)(Kl + key * KP + 16 * cc) = kr[jj]; *(LAS u32x4*)(Vl + key * KP + 16 * cc) = vr[jj]; }
.LBB0_938:
	v_and_b32_e32 v33, 31, v32
	s_lshl_b32 s22, s11, 10
	s_lshl_b32 s11, s11, 6
	v_mov_b32_e32 v15, 0
	v_or_b32_e32 v72, s34, v33
	s_and_b32 s22, s22, 0x7000
	s_and_b32 s27, s11, 0xc0
	s_andn2_b64 vcc, exec, s[0:1]
	v_mov_b32_e32 v14, v15
	v_mov_b32_e32 v13, v15
	v_mov_b32_e32 v12, v15
	v_mov_b32_e32 v11, v15
	v_mov_b32_e32 v10, v15
	v_mov_b32_e32 v9, v15
	v_mov_b32_e32 v8, v15
	v_mov_b32_e32 v7, v15
	v_mov_b32_e32 v6, v15
	v_mov_b32_e32 v5, v15
	v_mov_b32_e32 v4, v15
	v_mov_b32_e32 v3, v15
	v_mov_b32_e32 v2, v15
	v_mov_b32_e32 v1, v15
	v_mov_b32_e32 v0, v15
	v_mov_b32_e32 v31, v15
	v_mov_b32_e32 v30, v15
	v_mov_b32_e32 v29, v15
	v_mov_b32_e32 v28, v15
	v_mov_b32_e32 v27, v15
	v_mov_b32_e32 v26, v15
	v_mov_b32_e32 v25, v15
	v_mov_b32_e32 v24, v15
	v_mov_b32_e32 v23, v15
	v_mov_b32_e32 v22, v15
	v_mov_b32_e32 v21, v15
	v_mov_b32_e32 v20, v15
	v_mov_b32_e32 v19, v15
	v_mov_b32_e32 v18, v15
	v_mov_b32_e32 v17, v15
	v_mov_b32_e32 v16, v15
	s_cbranch_vccnz .LBB0_933
	v_add_u32_e32 v2, s22, v72
	v_mov_b64_e32 v[0:1], s[28:29]
	v_mad_i64_i32 v[0:1], s[0:1], v2, s82, v[0:1]
	s_lshl_b32 s0, s27, 1
	s_mov_b32 s1, s23
	v_lshl_add_u64 v[0:1], v[0:1], 0, s[0:1]
	v_lshlrev_b32_e32 v168, 4, v34
	v_lshl_add_u64 v[0:1], v[0:1], 0, v[168:169]
	global_load_dwordx4 v[48:51], v[0:1], off
	global_load_dwordx4 v[52:55], v[0:1], off offset:32
	global_load_dwordx4 v[56:59], v[0:1], off offset:64
	global_load_dwordx4 v[60:63], v[0:1], off offset:96
	s_mul_i32 s1, s22, 0x1800
	s_add_u32 s1, s28, s1
	v_and_b32_e32 v2, 63, v32
	s_addc_u32 s11, s29, 0
	s_add_u32 s0, s1, s0
	v_lshlrev_b32_e32 v0, 4, v2
	s_addc_u32 s1, s11, 0
	v_and_b32_e32 v0, 0x70, v0
	v_mov_b32_e32 v1, v169
	v_lshrrev_b32_e32 v101, 3, v2
	v_bfe_u32 v4, v32, 2, 2
	v_lshlrev_b32_e32 v3, 3, v2
	v_lshl_add_u64 v[74:75], s[0:1], 0, v[0:1]
	v_readlane_b32 s0, v254, 17
	v_cmp_gt_u32_e64 s[36:37], 32, v2
	v_and_or_b32 v4, v101, 4, v4
	v_lshlrev_b32_e32 v2, 1, v2
	v_mov_b32_e32 v1, s0
	s_movk_i32 s1, 0x90
	v_mul_u32_u24_e32 v4, 0x90, v4
	v_and_b32_e32 v2, 32, v2
	v_add_u32_e32 v0, s0, v0
	v_mad_u32_u24 v1, v33, s1, v1
	v_add3_u32 v2, s0, v4, v2
	v_and_b32_e32 v3, 24, v3
	v_mul_u32_u24_e32 v4, 0x90, v101
	v_mov_b32_e32 v102, 0
	v_mov_b32_e32 v73, v72
	v_mov_b32_e32 v103, s10
	s_waitcnt vmcnt(13)
	v_add_u32_e32 v104, v0, v4
	v_add_u32_e32 v105, v1, v168
	v_add_u32_e32 v106, v2, v3
	v_mov_b32_e32 v0, 0
	v_mov_b32_e32 v1, v102
	v_mov_b32_e32 v2, v102
	v_mov_b32_e32 v3, v102
	v_mov_b32_e32 v4, v102
	v_mov_b32_e32 v5, v102
	v_mov_b32_e32 v6, v102
	v_mov_b32_e32 v7, v102
	v_mov_b32_e32 v8, v102
	v_mov_b32_e32 v9, v102
	v_mov_b32_e32 v10, v102
	v_mov_b32_e32 v11, v102
	v_mov_b32_e32 v12, v102
	v_mov_b32_e32 v13, v102
	v_mov_b32_e32 v14, v102
	v_mov_b32_e32 v15, v102
	v_mov_b32_e32 v16, 0
	v_mov_b32_e32 v17, v102
	v_mov_b32_e32 v18, v102
	v_mov_b32_e32 v19, v102
	v_mov_b32_e32 v20, v102
	v_mov_b32_e32 v21, v102
	v_mov_b32_e32 v22, v102
	v_mov_b32_e32 v23, v102
	v_mov_b32_e32 v24, v102
	v_mov_b32_e32 v25, v102
	v_mov_b32_e32 v26, v102
	v_mov_b32_e32 v27, v102
	v_mov_b32_e32 v28, v102
	v_mov_b32_e32 v29, v102
	v_mov_b32_e32 v30, v102
	v_mov_b32_e32 v31, v102
	v_add_u32_e32 v113, s34, v101
	v_mad_u64_u32 v[160:161], s[0:1], v113, s82, v[74:75]
	v_add_u32_e32 v114, 8, v113
	v_add_u32_e32 v115, 16, v113
	v_add_u32_e32 v116, 24, v113
	v_mad_u64_u32 v[162:163], s[0:1], v114, s82, v[74:75]
	v_mad_u64_u32 v[164:165], s[0:1], v115, s82, v[74:75]
	v_mad_u64_u32 v[166:167], s[0:1], v116, s82, v[74:75]
	global_load_dwordx4 v[128:131], v[160:161], off offset:512
	global_load_dwordx4 v[132:135], v[160:161], off offset:1024
	global_load_dwordx4 v[136:139], v[162:163], off offset:512
	global_load_dwordx4 v[140:143], v[162:163], off offset:1024
	global_load_dwordx4 v[144:147], v[164:165], off offset:512
	global_load_dwordx4 v[148:151], v[164:165], off offset:1024
	global_load_dwordx4 v[152:155], v[166:167], off offset:512
	global_load_dwordx4 v[156:159], v[166:167], off offset:1024
.LBB0_940:
	s_waitcnt vmcnt(7)
	ds_write_b128 v104, v[128:131]
	s_waitcnt vmcnt(6)
	ds_write_b128 v104, v[132:135] offset:4608
	s_waitcnt vmcnt(5)
	ds_write_b128 v104, v[136:139] offset:1152
	s_waitcnt vmcnt(4)
	ds_write_b128 v104, v[140:143] offset:5760
	s_waitcnt vmcnt(3)
	ds_write_b128 v104, v[144:147] offset:2304
	s_waitcnt vmcnt(2)
	ds_write_b128 v104, v[148:151] offset:6912
	s_waitcnt vmcnt(1)
	ds_write_b128 v104, v[152:155] offset:3456
	s_waitcnt vmcnt(0)
	ds_write_b128 v104, v[156:159] offset:8064
	s_cmp_lt_i32 s34, 32
	s_cbranch_scc1 .Lsb_nopf
	v_add_u32_e32 v113, s34, v101
	v_add_u32_e32 v113, 0xffffffe0, v113
	v_mad_u64_u32 v[160:161], s[0:1], v113, s82, v[74:75]
	v_add_u32_e32 v114, 8, v113
	v_add_u32_e32 v115, 16, v113
	v_add_u32_e32 v116, 24, v113
	v_mad_u64_u32 v[162:163], s[0:1], v114, s82, v[74:75]
	v_mad_u64_u32 v[164:165], s[0:1], v115, s82, v[74:75]
	v_mad_u64_u32 v[166:167], s[0:1], v116, s82, v[74:75]
	global_load_dwordx4 v[128:131], v[160:161], off offset:512
	global_load_dwordx4 v[132:135], v[160:161], off offset:1024
	global_load_dwordx4 v[136:139], v[162:163], off offset:512
	global_load_dwordx4 v[140:143], v[162:163], off offset:1024
	global_load_dwordx4 v[144:147], v[164:165], off offset:512
	global_load_dwordx4 v[148:151], v[164:165], off offset:1024
	global_load_dwordx4 v[152:155], v[166:167], off offset:512
	global_load_dwordx4 v[156:159], v[166:167], off offset:1024
; #define LDS_WAIT() asm volatile("s_waitcnt lgkmcnt(0)" ::: "memory")
; DI void sb_unit(const Params& P, LAS char* lds, int b, int hd, int qb, int wave, int lane) {
;     ...
;         LDS_WAIT(); asm volatile("" ::: "memory");
;         const f32x16 s = qk_rows<0, 4>(Kl, 0, qf, r, h);
;         float l1m[16], ls[16];
;         unsigned vm = 0;
; #pragma unroll
;         for (int i = 0; i < 16; ++i) { const int kidx = kbase + (i & 3) + 8 * (i >> 2) + 4 * h; const bool ok = kidx < qpos; vm |= ok ? (1u << i) : 0u;
;             const float z = s[i] * 0.125f; const float sp = fmaxf(z, 0.f) + __logf(1.0f + __expf(-fabsf(z)));
;             l1m[i] = ok ? -sp : 0.f; ls[i] = z - sp; }
.Lsb_nopf:
	s_waitcnt lgkmcnt(0)
	ds_read_b128 v[32:35], v105
	ds_read_b128 v[64:67], v105 offset:32
	ds_read_b128 v[68:71], v105 offset:64
	ds_read_b128 v[76:79], v105 offset:96
	s_setprio 1
	s_waitcnt lgkmcnt(3)
	v_mfma_f32_32x32x16_bf16 v[32:47], v[32:35], v[48:51], 0
	s_waitcnt lgkmcnt(2)
	v_mfma_f32_32x32x16_bf16 v[32:47], v[64:67], v[52:55], v[32:47]
	s_waitcnt lgkmcnt(1)
	v_mfma_f32_32x32x16_bf16 v[32:47], v[68:71], v[56:59], v[32:47]
	s_waitcnt lgkmcnt(0)
	v_mfma_f32_32x32x16_bf16 v[32:47], v[76:79], v[60:63], v[32:47]
	s_setprio 0
	s_nop 10
	v_mul_f32_e32 v64, 0x3e000000, v32
	v_max_f32_e32 v65, 0, v64
	v_mul_f32_e64 v64, |v64|, s17
	v_exp_f32_e32 v64, v64
	v_mul_f32_e32 v70, 0x3e000000, v45
	v_mul_f32_e32 v78, 0x3e000000, v46
	v_mul_f32_e32 v82, 0x3e000000, v47
	v_add_f32_e32 v64, 1.0, v64
	v_cmp_gt_f32_e32 vcc, s21, v64
	s_nop 1
	v_cndmask_b32_e64 v66, 0, 32, vcc
	v_ldexp_f32 v64, v64, v66
	v_log_f32_e32 v64, v64
	s_nop 0
	v_mul_f32_e32 v66, 0x3f317217, v64
	v_fma_f32 v66, v64, s30, -v66
	v_fmac_f32_e32 v66, 0x3377d1cf, v64
	v_fmac_f32_e32 v66, 0x3f317217, v64
	v_cmp_lt_f32_e64 s[0:1], |v64|, s19
	s_nop 1
	v_cndmask_b32_e64 v64, v64, v66, s[0:1]
	v_cndmask_b32_e32 v66, 0, v211, vcc
	v_sub_f32_e32 v67, v64, v66
	v_mul_f32_e32 v64, 0x3e000000, v33
	v_max_f32_e32 v69, 0, v64
	v_mul_f32_e64 v64, |v64|, s17
	v_exp_f32_e32 v64, v64
	s_nop 0
	v_add_f32_e32 v64, 1.0, v64
	v_cmp_gt_f32_e32 vcc, s21, v64
	s_nop 1
	v_cndmask_b32_e64 v66, 0, 32, vcc
	v_ldexp_f32 v64, v64, v66
	v_log_f32_e32 v64, v64
	s_nop 0
	v_mul_f32_e32 v66, 0x3f317217, v64
	v_fma_f32 v66, v64, s30, -v66
	v_fmac_f32_e32 v66, 0x3377d1cf, v64
	v_fmac_f32_e32 v66, 0x3f317217, v64
	v_cmp_lt_f32_e64 s[0:1], |v64|, s19
	s_nop 1
	v_cndmask_b32_e64 v64, v64, v66, s[0:1]
	v_cndmask_b32_e32 v66, 0, v211, vcc
	v_sub_f32_e32 v71, v64, v66
	v_mul_f32_e32 v64, 0x3e000000, v34
	v_max_f32_e32 v77, 0, v64
	v_mul_f32_e64 v64, |v64|, s17
	v_exp_f32_e32 v64, v64
	s_nop 0
	v_add_f32_e32 v64, 1.0, v64
	v_cmp_gt_f32_e32 vcc, s21, v64
	s_nop 1
	v_cndmask_b32_e64 v66, 0, 32, vcc
	v_ldexp_f32 v64, v64, v66
	v_log_f32_e32 v64, v64
	s_nop 0
	v_mul_f32_e32 v66, 0x3f317217, v64
	v_fma_f32 v66, v64, s30, -v66
	v_fmac_f32_e32 v66, 0x3377d1cf, v64
	v_fmac_f32_e32 v66, 0x3f317217, v64
	v_cmp_lt_f32_e64 s[0:1], |v64|, s19
	s_nop 1
	v_cndmask_b32_e64 v64, v64, v66, s[0:1]
	v_cndmask_b32_e32 v66, 0, v211, vcc
	v_sub_f32_e32 v79, v64, v66
	v_mul_f32_e32 v64, 0x3e000000, v35
	v_max_f32_e32 v81, 0, v64
	v_mul_f32_e64 v64, |v64|, s17
	v_exp_f32_e32 v64, v64
	s_nop 0
	v_add_f32_e32 v64, 1.0, v64
	v_cmp_gt_f32_e32 vcc, s21, v64
	s_nop 1
	v_cndmask_b32_e64 v66, 0, 32, vcc
	v_ldexp_f32 v64, v64, v66
	v_log_f32_e32 v64, v64
	s_nop 0
	v_mul_f32_e32 v66, 0x3f317217, v64
	v_fma_f32 v66, v64, s30, -v66
	v_fmac_f32_e32 v66, 0x3377d1cf, v64
	v_fmac_f32_e32 v66, 0x3f317217, v64
	v_cmp_lt_f32_e64 s[0:1], |v64|, s19
	s_nop 1
	v_cndmask_b32_e64 v64, v64, v66, s[0:1]
	v_cndmask_b32_e32 v66, 0, v211, vcc
	v_sub_f32_e32 v83, v64, v66
	v_mul_f32_e32 v64, 0x3e000000, v36
	v_max_f32_e32 v85, 0, v64
	v_mul_f32_e64 v64, |v64|, s17
	v_exp_f32_e32 v64, v64
	s_nop 0
	v_add_f32_e32 v64, 1.0, v64
	v_cmp_gt_f32_e32 vcc, s21, v64
	s_nop 1
	v_cndmask_b32_e64 v66, 0, 32, vcc
	v_ldexp_f32 v64, v64, v66
	v_log_f32_e32 v64, v64
	s_nop 0
	v_mul_f32_e32 v66, 0x3f317217, v64
	v_fma_f32 v66, v64, s30, -v66
	v_fmac_f32_e32 v66, 0x3377d1cf, v64
	v_fmac_f32_e32 v66, 0x3f317217, v64
	v_cmp_lt_f32_e64 s[0:1], |v64|, s19
	s_nop 1
	v_cndmask_b32_e64 v64, v64, v66, s[0:1]
	v_cndmask_b32_e32 v66, 0, v211, vcc
	v_sub_f32_e32 v87, v64, v66
	v_mul_f32_e32 v64, 0x3e000000, v37
	v_max_f32_e32 v89, 0, v64
	v_mul_f32_e64 v64, |v64|, s17
	v_exp_f32_e32 v64, v64
	s_nop 0
	v_add_f32_e32 v64, 1.0, v64
	v_cmp_gt_f32_e32 vcc, s21, v64
	s_nop 1
	v_cndmask_b32_e64 v66, 0, 32, vcc
	v_ldexp_f32 v64, v64, v66
	v_log_f32_e32 v64, v64
	s_nop 0
	v_mul_f32_e32 v66, 0x3f317217, v64
	v_fma_f32 v66, v64, s30, -v66
	v_fmac_f32_e32 v66, 0x3377d1cf, v64
	v_fmac_f32_e32 v66, 0x3f317217, v64
	v_cmp_lt_f32_e64 s[0:1], |v64|, s19
	s_nop 1
	v_cndmask_b32_e64 v64, v64, v66, s[0:1]
	v_cndmask_b32_e32 v66, 0, v211, vcc
	v_sub_f32_e32 v91, v64, v66
	v_mul_f32_e32 v64, 0x3e000000, v38
	v_max_f32_e32 v93, 0, v64
	v_mul_f32_e64 v64, |v64|, s17
	v_exp_f32_e32 v64, v64
	s_nop 0
	v_add_f32_e32 v64, 1.0, v64
	v_cmp_gt_f32_e32 vcc, s21, v64
	s_nop 1
	v_cndmask_b32_e64 v66, 0, 32, vcc
	v_ldexp_f32 v64, v64, v66
	v_log_f32_e32 v64, v64
	s_nop 0
	v_mul_f32_e32 v66, 0x3f317217, v64
	v_fma_f32 v66, v64, s30, -v66
	v_fmac_f32_e32 v66, 0x3377d1cf, v64
	v_fmac_f32_e32 v66, 0x3f317217, v64
	v_cmp_lt_f32_e64 s[0:1], |v64|, s19
	s_nop 1
	v_cndmask_b32_e64 v64, v64, v66, s[0:1]
	v_cndmask_b32_e32 v66, 0, v211, vcc
	v_sub_f32_e32 v95, v64, v66
	v_mul_f32_e32 v64, 0x3e000000, v39
	v_max_f32_e32 v97, 0, v64
	v_mul_f32_e64 v64, |v64|, s17
	v_exp_f32_e32 v64, v64
	s_nop 0
	v_add_f32_e32 v64, 1.0, v64
	v_cmp_gt_f32_e32 vcc, s21, v64
	s_nop 1
	v_cndmask_b32_e64 v66, 0, 32, vcc
	v_ldexp_f32 v64, v64, v66
	v_log_f32_e32 v64, v64
	s_nop 0
	v_mul_f32_e32 v66, 0x3f317217, v64
	v_fma_f32 v66, v64, s30, -v66
	v_fmac_f32_e32 v66, 0x3377d1cf, v64
	v_fmac_f32_e32 v66, 0x3f317217, v64
	v_cmp_lt_f32_e64 s[0:1], |v64|, s19
	s_nop 1
	v_cndmask_b32_e64 v64, v64, v66, s[0:1]
	v_cndmask_b32_e32 v66, 0, v211, vcc
	v_sub_f32_e32 v99, v64, v66
	v_mul_f32_e32 v64, 0x3e000000, v40
	v_max_f32_e32 v84, 0, v64
	v_mul_f32_e64 v64, |v64|, s17
	v_exp_f32_e32 v64, v64
	s_nop 0
	v_add_f32_e32 v64, 1.0, v64
	v_cmp_gt_f32_e32 vcc, s21, v64
	s_nop 1
	v_cndmask_b32_e64 v66, 0, 32, vcc
	v_ldexp_f32 v64, v64, v66
	v_log_f32_e32 v64, v64
	s_nop 0
; DI void sb_unit(const Params& P, LAS char* lds, int b, int hd, int qb, int wave, int lane) {
;     ...
;         for (int i = 0; i < 16; ++i) { const int kidx = kbase + (i & 3) + 8 * (i >> 2) + 4 * h; const bool ok = kidx < qpos; vm |= ok ? (1u << i) : 0u;
;             const float z = s[i] * 0.125f; const float sp = fmaxf(z, 0.f) + __logf(1.0f + __expf(-fabsf(z)));
;             l1m[i] = ok ? -sp : 0.f; ls[i] = z - sp; }
;         float G[4], Gp[4], tot[4];
; #pragma unroll
;         for (int g = 0; g < 4; ++g) { G[g] = (l1m[4 * g] + l1m[4 * g + 1]) + (l1m[4 * g + 2] + l1m[4 * g + 3]); Gp[g] = shx32(G[g], lane); tot[g] = G[g] + Gp[g]; }
	v_mul_f32_e32 v66, 0x3f317217, v64
	v_fma_f32 v66, v64, s30, -v66
	v_fmac_f32_e32 v66, 0x3377d1cf, v64
	v_fmac_f32_e32 v66, 0x3f317217, v64
	v_cmp_lt_f32_e64 s[0:1], |v64|, s19
	s_nop 1
	v_cndmask_b32_e64 v64, v64, v66, s[0:1]
	v_cndmask_b32_e32 v66, 0, v211, vcc
	v_sub_f32_e32 v86, v64, v66
	v_mul_f32_e32 v64, 0x3e000000, v41
	v_max_f32_e32 v88, 0, v64
	v_mul_f32_e64 v64, |v64|, s17
	v_exp_f32_e32 v64, v64
	s_nop 0
	v_add_f32_e32 v64, 1.0, v64
	v_cmp_gt_f32_e32 vcc, s21, v64
	s_nop 1
	v_cndmask_b32_e64 v66, 0, 32, vcc
	v_ldexp_f32 v64, v64, v66
	v_log_f32_e32 v64, v64
	s_nop 0
	v_mul_f32_e32 v66, 0x3f317217, v64
	v_fma_f32 v66, v64, s30, -v66
	v_fmac_f32_e32 v66, 0x3377d1cf, v64
	v_fmac_f32_e32 v66, 0x3f317217, v64
	v_cmp_lt_f32_e64 s[0:1], |v64|, s19
	s_nop 1
	v_cndmask_b32_e64 v64, v64, v66, s[0:1]
	v_cndmask_b32_e32 v66, 0, v211, vcc
	v_sub_f32_e32 v90, v64, v66
	v_mul_f32_e32 v64, 0x3e000000, v42
	v_max_f32_e32 v92, 0, v64
	v_mul_f32_e64 v64, |v64|, s17
	v_exp_f32_e32 v64, v64
	s_nop 0
	v_add_f32_e32 v64, 1.0, v64
	v_cmp_gt_f32_e32 vcc, s21, v64
	s_nop 1
	v_cndmask_b32_e64 v66, 0, 32, vcc
	v_ldexp_f32 v64, v64, v66
	v_log_f32_e32 v64, v64
	s_nop 0
	v_mul_f32_e32 v66, 0x3f317217, v64
	v_fma_f32 v66, v64, s30, -v66
	v_fmac_f32_e32 v66, 0x3377d1cf, v64
	v_fmac_f32_e32 v66, 0x3f317217, v64
	v_cmp_lt_f32_e64 s[0:1], |v64|, s19
	s_nop 1
	v_cndmask_b32_e64 v64, v64, v66, s[0:1]
	v_cndmask_b32_e32 v66, 0, v211, vcc
	v_sub_f32_e32 v94, v64, v66
	v_mul_f32_e32 v64, 0x3e000000, v43
	v_max_f32_e32 v96, 0, v64
	v_mul_f32_e64 v64, |v64|, s17
	v_exp_f32_e32 v64, v64
	s_nop 0
	v_add_f32_e32 v64, 1.0, v64
	v_cmp_gt_f32_e32 vcc, s21, v64
	s_nop 1
	v_cndmask_b32_e64 v66, 0, 32, vcc
	v_ldexp_f32 v64, v64, v66
	v_log_f32_e32 v64, v64
	s_nop 0
	v_mul_f32_e32 v66, 0x3f317217, v64
	v_fma_f32 v66, v64, s30, -v66
	v_fmac_f32_e32 v66, 0x3377d1cf, v64
	v_fmac_f32_e32 v66, 0x3f317217, v64
	v_cmp_lt_f32_e64 s[0:1], |v64|, s19
	s_nop 1
	v_cndmask_b32_e64 v64, v64, v66, s[0:1]
	v_cndmask_b32_e32 v66, 0, v211, vcc
	v_sub_f32_e32 v98, v64, v66
	v_mul_f32_e32 v66, 0x3e000000, v44
	v_max_f32_e32 v64, 0, v66
	v_mul_f32_e64 v66, |v66|, s17
	v_exp_f32_e32 v66, v66
	s_nop 0
	v_add_f32_e32 v66, 1.0, v66
	v_cmp_gt_f32_e32 vcc, s21, v66
	s_nop 1
	v_cndmask_b32_e64 v68, 0, 32, vcc
	v_ldexp_f32 v66, v66, v68
	v_log_f32_e32 v66, v66
	s_nop 0
	v_mul_f32_e32 v68, 0x3f317217, v66
	v_fma_f32 v68, v66, s30, -v68
	v_fmac_f32_e32 v68, 0x3377d1cf, v66
	v_fmac_f32_e32 v68, 0x3f317217, v66
	v_cmp_lt_f32_e64 s[0:1], |v66|, s19
	s_nop 1
	v_cndmask_b32_e64 v66, v66, v68, s[0:1]
	v_cndmask_b32_e32 v68, 0, v211, vcc
	v_sub_f32_e32 v66, v66, v68
	v_max_f32_e32 v68, 0, v70
	v_mul_f32_e64 v70, |v70|, s17
	v_exp_f32_e32 v70, v70
	s_nop 0
	v_add_f32_e32 v70, 1.0, v70
	v_cmp_gt_f32_e32 vcc, s21, v70
	s_nop 1
	v_cndmask_b32_e64 v76, 0, 32, vcc
	v_ldexp_f32 v70, v70, v76
	v_log_f32_e32 v70, v70
	s_nop 0
	v_mul_f32_e32 v76, 0x3f317217, v70
	v_fma_f32 v76, v70, s30, -v76
	v_fmac_f32_e32 v76, 0x3377d1cf, v70
	v_fmac_f32_e32 v76, 0x3f317217, v70
	v_cmp_lt_f32_e64 s[0:1], |v70|, s19
	s_nop 1
	v_cndmask_b32_e64 v70, v70, v76, s[0:1]
	v_cndmask_b32_e32 v76, 0, v211, vcc
	v_sub_f32_e32 v70, v70, v76
	v_max_f32_e32 v76, 0, v78
	v_mul_f32_e64 v78, |v78|, s17
	v_exp_f32_e32 v78, v78
	v_pk_add_f32 v[68:69], v[68:69], v[70:71]
	v_add_f32_e32 v78, 1.0, v78
	v_cmp_gt_f32_e32 vcc, s21, v78
	s_nop 1
	v_cndmask_b32_e64 v80, 0, 32, vcc
	v_ldexp_f32 v78, v78, v80
	v_log_f32_e32 v78, v78
	s_nop 0
	v_mul_f32_e32 v80, 0x3f317217, v78
	v_fma_f32 v80, v78, s30, -v80
	v_fmac_f32_e32 v80, 0x3377d1cf, v78
	v_fmac_f32_e32 v80, 0x3f317217, v78
	v_cmp_lt_f32_e64 s[0:1], |v78|, s19
	s_nop 1
	v_cndmask_b32_e64 v78, v78, v80, s[0:1]
	v_cndmask_b32_e32 v80, 0, v211, vcc
	v_sub_f32_e32 v78, v78, v80
	v_max_f32_e32 v80, 0, v82
	v_mul_f32_e64 v82, |v82|, s17
	v_exp_f32_e32 v82, v82
	s_nop 0
	v_add_f32_e32 v82, 1.0, v82
	v_cmp_gt_f32_e32 vcc, s21, v82
	s_nop 1
	v_cndmask_b32_e64 v107, 0, 32, vcc
	v_ldexp_f32 v82, v82, v107
	v_log_f32_e32 v82, v82
	s_nop 0
	v_mul_f32_e32 v107, 0x3f317217, v82
	v_fma_f32 v107, v82, s30, -v107
	v_fmac_f32_e32 v107, 0x3377d1cf, v82
	v_fmac_f32_e32 v107, 0x3f317217, v82
	v_cmp_lt_f32_e64 s[0:1], |v82|, s19
	s_nop 1
	v_cndmask_b32_e64 v82, v82, v107, s[0:1]
	v_cndmask_b32_e32 v107, 0, v211, vcc
	v_sub_f32_e32 v82, v82, v107
	v_add_u32_e32 v107, s34, v100
	v_or_b32_e32 v70, 26, v107
	v_or_b32_e32 v109, 25, v107
	v_cmp_lt_i32_e64 s[60:61], v70, v72
	v_pk_add_f32 v[70:71], v[76:77], v[78:79]
	v_cmp_lt_i32_e64 s[58:59], v109, v72
	v_fma_f32 v109, v33, s20, -v69
	v_or_b32_e32 v33, 2, v107
	v_fma_f32 v111, v34, s20, -v71
	v_or_b32_e32 v34, 27, v107
	v_cmp_lt_i32_e64 s[44:45], v33, v73
	v_or_b32_e32 v33, 3, v107
	v_cmp_lt_i32_e64 s[62:63], v34, v72
	v_pk_add_f32 v[76:77], v[80:81], v[82:83]
	v_or_b32_e32 v34, 16, v107
	v_cmp_lt_i32_e64 s[50:51], v33, v73
	v_fma_f32 v82, v35, s20, -v77
	v_or_b32_e32 v33, 8, v107
	v_cmp_lt_i32_e32 vcc, v34, v72
	v_pk_add_f32 v[34:35], v[84:85], v[86:87]
	v_or_b32_e32 v78, 17, v107
	v_cmp_lt_i32_e64 s[48:49], v33, v73
	v_fma_f32 v33, v36, s20, -v35
	v_or_b32_e32 v36, 9, v107
	v_cmp_lt_i32_e64 s[0:1], v78, v72
	v_pk_add_f32 v[78:79], v[88:89], v[90:91]
	v_cmp_lt_i32_e64 s[52:53], v36, v73
	v_fma_f32 v85, v37, s20, -v79
	v_or_b32_e32 v36, 10, v107
	v_or_b32_e32 v37, 18, v107
	v_cmp_lt_i32_e64 s[38:39], v37, v72
	v_cmp_lt_i32_e64 s[54:55], v36, v73
	v_pk_add_f32 v[36:37], v[92:93], v[94:95]
	v_or_b32_e32 v80, 19, v107
	v_fma_f32 v87, v38, s20, -v37
	v_or_b32_e32 v38, 11, v107
	v_cmp_lt_i32_e64 s[40:41], v80, v72
	v_cmp_lt_i32_e64 s[56:57], v38, v73
	v_pk_add_f32 v[80:81], v[96:97], v[98:99]
; DI void sb_unit(const Params& P, LAS char* lds, int b, int hd, int qb, int wave, int lane) {
;     ...
;         float G[4], Gp[4], tot[4];
; #pragma unroll
;         for (int g = 0; g < 4; ++g) { G[g] = (l1m[4 * g] + l1m[4 * g + 1]) + (l1m[4 * g + 2] + l1m[4 * g + 3]); Gp[g] = shx32(G[g], lane); tot[g] = G[g] + Gp[g]; }
;         float aft[4];
;         aft[3] = (h == 0) ? Gp[3] : 0.f;
;         aft[2] = tot[3] + ((h == 0) ? Gp[2] : 0.f);
;         aft[1] = tot[3] + tot[2] + ((h == 0) ? Gp[1] : 0.f);
;         aft[0] = tot[3] + tot[2] + tot[1] + ((h == 0) ? Gp[0] : 0.f);
;         float p[16];
; #pragma unroll
;         for (int g = 0; g < 4; ++g) {
;             const float base = carry + aft[g];
;             const float w3 = 0.f, w2 = l1m[4 * g + 3], w1 = w2 + l1m[4 * g + 2], w0 = w1 + l1m[4 * g + 1];
;             p[4 * g + 0] = ((vm >> (4 * g + 0)) & 1u) ? __expf(ls[4 * g + 0] + base + w0) : 0.f;
;             p[4 * g + 1] = ((vm >> (4 * g + 1)) & 1u) ? __expf(ls[4 * g + 1] + base + w1) : 0.f;
;             p[4 * g + 2] = ((vm >> (4 * g + 2)) & 1u) ? __expf(ls[4 * g + 2] + base + w2) : 0.f;
;             p[4 * g + 3] = ((vm >> (4 * g + 3)) & 1u) ? __expf(ls[4 * g + 3] + base + w3) : 0.f;
	v_or_b32_e32 v108, 1, v107
	v_fma_f32 v89, v39, s20, -v81
	v_cndmask_b32_e64 v39, 0, -v35, s[48:49]
	v_cndmask_b32_e64 v38, 0, -v34, vcc
	v_fma_f32 v91, v40, s20, -v34
	v_cndmask_b32_e64 v35, 0, -v79, s[52:53]
	v_cndmask_b32_e64 v34, 0, -v78, s[0:1]
	v_fma_f32 v78, v41, s20, -v78
	v_cndmask_b32_e64 v41, 0, -v37, s[54:55]
	v_cndmask_b32_e64 v40, 0, -v36, s[38:39]
	v_fma_f32 v93, v42, s20, -v36
	v_cndmask_b32_e64 v37, 0, -v81, s[56:57]
	v_cndmask_b32_e64 v36, 0, -v80, s[40:41]
	v_add_u32_e32 v42, 24, v107
	v_cmp_lt_i32_e64 s[42:43], v108, v73
	v_fma_f32 v80, v43, s20, -v80
	v_cmp_lt_i32_e64 s[64:65], v107, v73
	v_cmp_lt_i32_e64 s[66:67], v42, v72
	v_pk_add_f32 v[42:43], v[64:65], v[66:67]
	v_pk_add_f32 v[38:39], v[38:39], v[34:35]
	v_pk_add_f32 v[40:41], v[40:41], v[36:37]
	v_cndmask_b32_e64 v65, 0, -v43, s[64:65]
	v_cndmask_b32_e64 v64, 0, -v42, s[66:67]
	v_fma_f32 v95, v44, s20, -v42
	v_cndmask_b32_e64 v67, 0, -v69, s[42:43]
	v_cndmask_b32_e64 v66, 0, -v68, s[58:59]
	v_fma_f32 v96, v45, s20, -v68
	v_cndmask_b32_e64 v45, 0, -v71, s[44:45]
	v_cndmask_b32_e64 v44, 0, -v70, s[60:61]
	v_cndmask_b32_e64 v69, 0, -v77, s[50:51]
	v_cndmask_b32_e64 v68, 0, -v76, s[62:63]
	v_pk_add_f32 v[38:39], v[38:39], v[40:41]
	v_fma_f32 v98, v46, s20, -v70
	v_fma_f32 v76, v47, s20, -v76
	v_pk_add_f32 v[46:47], v[64:65], v[66:67]
	v_pk_add_f32 v[44:45], v[44:45], v[68:69]
	v_mov_b32_e32 v64, v39
	v_mov_b32_e32 v65, v39
	v_mov_b32_e32 v77, v38
	v_mov_b32_e32 v107, v38
	v_pk_add_f32 v[46:47], v[46:47], v[44:45]
	v_permlane32_swap_b32_e32 v64, v65
	v_permlane32_swap_b32_e32 v77, v107
	v_mov_b32_e32 v70, v47
	v_mov_b32_e32 v71, v47
	v_cndmask_b32_e64 v65, v64, v65, s[36:37]
	v_cndmask_b32_e64 v64, v77, v107, s[36:37]
	v_mov_b32_e32 v77, v46
	v_mov_b32_e32 v107, v46
	v_cndmask_b32_e64 v84, 0, 32, s[52:53]
	v_cndmask_b32_e64 v79, 0, v199, s[38:39]
	v_cndmask_b32_e64 v94, 0, v200, s[40:41]
	v_permlane32_swap_b32_e32 v70, v71
	v_permlane32_swap_b32_e32 v77, v107
	v_cndmask_b32_e64 v112, 0, 8, s[50:51]
	v_cndmask_b32_e64 v83, 0, 16, s[48:49]
	v_cndmask_b32_e64 v71, v70, v71, s[36:37]
	v_cndmask_b32_e64 v70, v77, v107, s[36:37]
	v_or3_b32 v77, v84, v79, v94
	v_cndmask_b32_e64 v110, 0, 4, s[44:45]
	v_cndmask_b32_e64 v86, 0, 64, s[54:55]
	v_or3_b32 v77, v83, v112, v77
	v_cndmask_b32_e64 v108, 0, 2, s[42:43]
	v_cndmask_b32_e64 v88, 0, v196, s[56:57]
	v_or3_b32 v77, v110, v86, v77
	v_cndmask_b32_e32 v90, 0, v197, vcc
	v_cndmask_b32_e64 v92, 0, v198, s[0:1]
	v_or3_b32 v77, v108, v88, v77
	v_cndmask_b32_e64 v81, 0, v201, s[66:67]
	v_cndmask_b32_e64 v42, 0, v202, s[58:59]
	v_or3_b32 v77, v90, v92, v77
	v_pk_add_f32 v[38:39], v[38:39], v[64:65]
	v_pk_add_f32 v[46:47], v[46:47], v[70:71]
	v_or3_b32 v77, v81, v42, v77
	v_cndmask_b32_e64 v42, 0, v64, s[36:37]
	v_add_f32_e32 v64, v42, v46
	v_pk_add_f32 v[46:47], v[38:39], v[46:47]
	v_cndmask_b32_e64 v42, 0, v65, s[36:37]
	v_add_f32_e32 v38, v39, v46
	v_cndmask_b32_e64 v39, 0, v71, s[36:37]
	v_add_f32_e32 v38, v39, v38
	v_add_f32_e32 v65, v42, v46
	v_add_f32_e32 v39, v102, v38
	v_fma_f32 v43, v32, s20, -v43
	v_mov_b32_e32 v42, v67
	v_mov_b32_e32 v38, v45
	v_pk_add_f32 v[42:43], v[42:43], v[38:39]
	v_mov_b32_e32 v38, v41
	v_add_f32_e32 v32, v42, v43
	v_mul_f32_e32 v32, 0x3fb8aa3b, v32
	v_exp_f32_e32 v32, v32
	v_cndmask_b32_e64 v70, 0, v70, s[36:37]
	v_mov_b32_e32 v67, v95
	v_cndmask_b32_e64 v97, 0, v203, s[60:61]
	v_cndmask_b32_e64 v42, 0, v32, s[64:65]
	v_add_f32_e32 v32, v109, v39
	v_add_f32_e32 v32, v45, v32
	v_mul_f32_e32 v32, 0x3fb8aa3b, v32
	v_exp_f32_e32 v32, v32
	v_add_f32_e32 v45, v102, v70
	v_cndmask_b32_e64 v99, 0, v204, s[62:63]
	v_or3_b32 v79, v97, v99, v77
	v_cndmask_b32_e64 v43, 0, v32, s[42:43]
	v_add_f32_e32 v32, v111, v39
	v_add_f32_e32 v32, v69, v32
	v_mul_f32_e32 v32, 0x3fb8aa3b, v32
	v_exp_f32_e32 v32, v32
	s_nop 0
	v_cndmask_b32_e64 v69, 0, v32, s[44:45]
; DI void sb_unit(const Params& P, LAS char* lds, int b, int hd, int qb, int wave, int lane) {
;     ...
;         for (int g = 0; g < 4; ++g) {
;             const float base = carry + aft[g];
;             const float w3 = 0.f, w2 = l1m[4 * g + 3], w1 = w2 + l1m[4 * g + 2], w0 = w1 + l1m[4 * g + 1];
;             p[4 * g + 0] = ((vm >> (4 * g + 0)) & 1u) ? __expf(ls[4 * g + 0] + base + w0) : 0.f;
;             p[4 * g + 1] = ((vm >> (4 * g + 1)) & 1u) ? __expf(ls[4 * g + 1] + base + w1) : 0.f;
;             p[4 * g + 2] = ((vm >> (4 * g + 2)) & 1u) ? __expf(ls[4 * g + 2] + base + w2) : 0.f;
;             p[4 * g + 3] = ((vm >> (4 * g + 3)) & 1u) ? __expf(ls[4 * g + 3] + base + w3) : 0.f;
;         }
;         carry += (tot[0] + tot[1]) + (tot[2] + tot[3]);
;         bf16x8 pf[2]; pack_p(p, pf);
;         pv_rows(o, Vl, 0, pf, lane);
;         asm volatile("" ::: "memory");
;         if (__builtin_amdgcn_ballot_w64(carry >= -120.0f) == 0ull) break;
;     }
	v_add_f32_e32 v32, v82, v39
	v_add_f32_e32 v32, 0, v32
	v_mul_f32_e32 v32, 0x3fb8aa3b, v32
	v_exp_f32_e32 v32, v32
	v_add_f32_e32 v39, v102, v65
	v_cndmask_b32_e64 v71, 0, v32, s[50:51]
	v_mov_b32_e32 v32, v35
	v_pk_add_f32 v[32:33], v[32:33], v[38:39]
	v_mov_b32_e32 v35, v91
	v_add_f32_e32 v32, v32, v33
	v_mul_f32_e32 v32, 0x3fb8aa3b, v32
	v_exp_f32_e32 v32, v32
	s_nop 0
	v_cndmask_b32_e64 v38, 0, v32, s[48:49]
	v_add_f32_e32 v32, v85, v39
	v_add_f32_e32 v32, v41, v32
	v_mul_f32_e32 v32, 0x3fb8aa3b, v32
	v_exp_f32_e32 v32, v32
	v_add_f32_e32 v41, v102, v64
	v_cndmask_b32_e64 v65, 0, v32, s[52:53]
	v_add_f32_e32 v32, v87, v39
	v_add_f32_e32 v32, v37, v32
	v_mul_f32_e32 v32, 0x3fb8aa3b, v32
	v_exp_f32_e32 v32, v32
	v_cvt_pk_bf16_f32 v37, v69, v71
	v_cvt_pk_bf16_f32 v38, v38, v65
	v_cndmask_b32_e64 v81, 0, v32, s[54:55]
	v_add_f32_e32 v32, v89, v39
	v_add_f32_e32 v32, 0, v32
	v_mul_f32_e32 v32, 0x3fb8aa3b, v32
	v_exp_f32_e32 v32, v32
	s_nop 0
	v_cndmask_b32_e64 v39, 0, v32, s[56:57]
	v_pk_add_f32 v[32:33], v[34:35], v[40:41]
	v_cvt_pk_bf16_f32 v39, v81, v39
	v_add_f32_e32 v32, v32, v33
	v_mul_f32_e32 v32, 0x3fb8aa3b, v32
	v_exp_f32_e32 v32, v32
	s_nop 0
	v_cndmask_b32_e32 v34, 0, v32, vcc
	v_add_f32_e32 v32, v78, v41
	v_add_f32_e32 v32, v40, v32
	v_mul_f32_e32 v32, 0x3fb8aa3b, v32
	v_exp_f32_e32 v32, v32
	s_nop 0
	v_cndmask_b32_e64 v35, 0, v32, s[0:1]
	v_add_f32_e32 v32, v93, v41
	v_add_f32_e32 v32, v36, v32
	v_mul_f32_e32 v32, 0x3fb8aa3b, v32
	v_exp_f32_e32 v32, v32
	v_cvt_pk_bf16_f32 v36, v42, v43
	v_cndmask_b32_e64 v40, 0, v32, s[38:39]
	v_add_f32_e32 v32, v80, v41
	v_add_f32_e32 v32, 0, v32
	v_mul_f32_e32 v32, 0x3fb8aa3b, v32
	v_exp_f32_e32 v32, v32
	s_nop 0
	v_cndmask_b32_e64 v41, 0, v32, s[40:41]
	v_pk_add_f32 v[32:33], v[66:67], v[44:45]
	s_nop 0
	v_add_f32_e32 v32, v32, v33
	v_mul_f32_e32 v32, 0x3fb8aa3b, v32
	v_exp_f32_e32 v32, v32
	v_and_b32_e32 v33, 0x1000, v77
	v_cmp_ne_u32_e32 vcc, 0, v33
	v_and_b32_e32 v33, 0x2000, v77
	s_nop 0
	v_cndmask_b32_e32 v64, 0, v32, vcc
	v_add_f32_e32 v32, v96, v45
	v_add_f32_e32 v32, v44, v32
	v_mul_f32_e32 v32, 0x3fb8aa3b, v32
	v_exp_f32_e32 v32, v32
	v_cmp_ne_u32_e32 vcc, 0, v33
	v_and_b32_e32 v33, 0x4000, v79
	s_nop 0
	v_cndmask_b32_e32 v44, 0, v32, vcc
	v_add_f32_e32 v32, v98, v45
	v_add_f32_e32 v32, v68, v32
	v_mul_f32_e32 v32, 0x3fb8aa3b, v32
	v_exp_f32_e32 v32, v32
	v_cmp_ne_u32_e32 vcc, 0, v33
	v_and_b32_e32 v33, 0x8000, v79
	s_nop 0
	v_cndmask_b32_e32 v66, 0, v32, vcc
	v_add_f32_e32 v32, v76, v45
	v_add_f32_e32 v32, 0, v32
	v_mul_f32_e32 v32, 0x3fb8aa3b, v32
	v_exp_f32_e32 v32, v32
	v_cmp_ne_u32_e32 vcc, 0, v33
	v_cvt_pk_bf16_f32 v33, v40, v41
	s_nop 0
	v_cndmask_b32_e32 v45, 0, v32, vcc
	v_add_f32_e32 v32, v46, v47
	v_add_f32_e32 v102, v102, v32
	v_cvt_pk_bf16_f32 v32, v34, v35
	v_cvt_pk_bf16_f32 v34, v64, v44
	v_cvt_pk_bf16_f32 v35, v66, v45
	ds_read_b64_tr_b16 v[44:45], v106 offset:4608
	ds_read_b64_tr_b16 v[46:47], v106 offset:5760
	ds_read_b64_tr_b16 v[40:41], v106 offset:6912
	ds_read_b64_tr_b16 v[42:43], v106 offset:8064
	ds_read_b64_tr_b16 v[64:65], v106 offset:4672
	ds_read_b64_tr_b16 v[66:67], v106 offset:5824
	ds_read_b64_tr_b16 v[68:69], v106 offset:6976
	ds_read_b64_tr_b16 v[70:71], v106 offset:8128
	s_setprio 1
	s_waitcnt lgkmcnt(6)
	v_mfma_f32_32x32x16_bf16 v[16:31], v[44:47], v[36:39], v[16:31]
	s_waitcnt lgkmcnt(2)
	v_mfma_f32_32x32x16_bf16 v[0:15], v[64:67], v[36:39], v[0:15]
	v_mfma_f32_32x32x16_bf16 v[16:31], v[40:43], v[32:35], v[16:31]
	s_waitcnt lgkmcnt(0)
	v_mfma_f32_32x32x16_bf16 v[0:15], v[68:71], v[32:35], v[0:15]
	s_setprio 0
	s_mov_b32 s0, 0xc2f00000
	v_cmp_le_f32_e32 vcc, s0, v102
	s_cmp_lg_u64 vcc, 0
	s_cselect_b64 s[0:1], -1, 0
	v_add_co_u32_e32 v103, vcc, -1, v103
	s_and_b64 s[0:1], vcc, s[0:1]
	s_sub_i32 s34, s34, 32
	s_and_b64 vcc, exec, s[0:1]
	s_cbranch_vccnz .LBB0_940
	v_mov_b32_e32 v168, v100
	s_branch .LBB0_933
